# P2a S3 epilogue: the per-register scalar reads (gc, beta) issued once early in the K loop instead of 28 read+wait pairs
# speedup vs baseline: 1.0090x; 1.0015x over previous
; #define LAS __attribute__((address_space(3)))
; #define MFMA32(a, b, c) __builtin_amdgcn_mfma_f32_32x32x16_bf16((a), (b), (c), 0, 0, 0)
; __device__ __forceinline__ unsigned pkbf(float a, float b) { bf16x2_t v = __builtin_convertvector((f32x2_t){a, b}, bf16x2_t); return __builtin_bit_cast(unsigned, v); }
; __device__ __forceinline__ void gdn_prep_phase(LAS unsigned char* lds, const GdnPrepArgs& A, int bid, int G, const unsigned char* zero_page) {
;     ...
;     {
;         const int which = w >> 2, rt = (w >> 1) & 1, ct = w & 1, r = lane & 31, hh = lane >> 5;
;         const LAS unsigned char* ia = lds + (which ? L_QN : L_KN) + (32 * rt + r) * QS_ + 16 * hh;
;         const LAS unsigned char* ib = lds + L_KN + (32 * ct + r) * QS_ + 16 * hh;
;         f32x16 acc = zero16();
; #pragma unroll
;         for (int ks = 0; ks < 8; ++ks) acc = MFMA32(*(const LAS bf16x8*)(ia + 32 * ks), *(const LAS bf16x8*)(ib + 32 * ks), acc);
;         const LAS float* sc = (const LAS float*)(lds + L_SC);
;         const int j = 32 * ct + r; const float gfj = sc[j], gbj = sc[64 + j];
; #pragma unroll
;         for (int reg = 0; reg < 16; ++reg) {
;             const int i = 32 * rt + (reg & 3) + 8 * (reg >> 2) + 4 * hh; const float val = acc[reg];
;             const float ef = __expf(sc[i] - gfj), eb = __expf(sc[64 + i] - gbj);
;             if (which == 0) {
;                 const float lf = (i > j) ? sc[128 + i] * val * ef : 0.f, lb = (i < j) ? sc[192 + i] * val * eb : 0.f;
;                 ((LAS float*)(lds + L_LPF))[i * 64 + (j & 3) * 16 + (j >> 2)] = lf;
;                 const int i2 = 63 - i, j2 = 63 - j;
;                 ((LAS float*)(lds + L_LPB))[i2 * 64 + (j2 & 3) * 16 + (j2 >> 2)] = lb;
;             } else {
;                 const float af = (i >= j) ? QSCALE * val * ef : 0.f, ab = (i <= j) ? QSCALE * val * eb : 0.f;
;                 *(LAS unsigned short*)(lds + L_AF + i * AS_ + j * 2) = (unsigned short)(pkbf(af, 0.f) & 0xffffu);
;                 *(LAS unsigned short*)(lds + L_AB + i * AS_ + j * 2) = (unsigned short)(pkbf(ab, 0.f) & 0xffffu);
;             }
;         }
.LBB0_209:
	ds_read_b128 v[2:5], v190
	ds_read_b128 v[6:9], v191
	ds_read_b128 v[32:35], v190 offset:32
	ds_read_b128 v[36:39], v191 offset:32
	s_mov_b64 s[46:47], -1
	s_and_b64 vcc, exec, s[4:5]
	s_waitcnt lgkmcnt(2)
	v_mfma_f32_32x32x16_bf16 v[2:17], v[2:5], v[6:9], 0
	s_waitcnt lgkmcnt(0)
	v_mfma_f32_32x32x16_bf16 v[2:17], v[32:35], v[36:39], v[2:17]
	ds_read_b128 v[32:35], v190 offset:64
	ds_read_b128 v[36:39], v191 offset:64
	ds_read2st64_b32 v[136:137], v72 offset1:1
	ds_read2st64_b32 v[138:139], v74 offset1:1
	ds_read2st64_b32 v[140:141], v76 offset1:1
	ds_read2st64_b32 v[142:143], v78 offset1:1
	ds_read2st64_b32 v[144:145], v80 offset1:1
	ds_read2st64_b32 v[146:147], v82 offset1:1
	ds_read2st64_b32 v[148:149], v84 offset1:1
	ds_read2st64_b32 v[150:151], v86 offset1:1
	ds_read2st64_b32 v[152:153], v88 offset1:1
	ds_read2st64_b32 v[154:155], v90 offset1:1
	ds_read2st64_b32 v[156:157], v92 offset1:1
	ds_read2st64_b32 v[158:159], v94 offset1:1
	ds_read2st64_b32 v[160:161], v96 offset1:1
	ds_read2st64_b32 v[162:163], v98 offset1:1
	ds_read2st64_b32 v[174:175], v100 offset1:1
	ds_read2st64_b32 v[176:177], v102 offset1:1
	ds_read2st64_b32 v[178:179], v72 offset0:2 offset1:3
	ds_read2st64_b32 v[180:181], v74 offset0:2 offset1:3
	ds_read2st64_b32 v[182:183], v76 offset0:2 offset1:3
	ds_read2st64_b32 v[230:231], v78 offset0:2 offset1:3
	ds_read2st64_b32 v[232:233], v80 offset0:2 offset1:3
	ds_read2st64_b32 v[234:235], v82 offset0:2 offset1:3
	ds_read2st64_b32 v[236:237], v84 offset0:2 offset1:3
	ds_read2st64_b32 v[238:239], v86 offset0:2 offset1:3
	ds_read2st64_b32 v[240:241], v88 offset0:2 offset1:3
	ds_read2st64_b32 v[242:243], v90 offset0:2 offset1:3
	ds_read2st64_b32 v[244:245], v92 offset0:2 offset1:3
	ds_read2st64_b32 v[248:249], v94 offset0:2 offset1:3
	s_nop 0
	s_waitcnt lgkmcnt(0)
	v_mfma_f32_32x32x16_bf16 v[2:17], v[32:35], v[36:39], v[2:17]
	ds_read_b128 v[32:35], v190 offset:96
	ds_read_b128 v[36:39], v191 offset:96
	s_waitcnt lgkmcnt(0)
	v_mfma_f32_32x32x16_bf16 v[2:17], v[32:35], v[36:39], v[2:17]
	ds_read_b128 v[32:35], v190 offset:128
	ds_read_b128 v[36:39], v191 offset:128
	s_waitcnt lgkmcnt(0)
	v_mfma_f32_32x32x16_bf16 v[2:17], v[32:35], v[36:39], v[2:17]
	ds_read_b128 v[32:35], v190 offset:160
	ds_read_b128 v[36:39], v191 offset:160
	s_waitcnt lgkmcnt(0)
	v_mfma_f32_32x32x16_bf16 v[2:17], v[32:35], v[36:39], v[2:17]
	ds_read_b128 v[34:37], v190 offset:192
	ds_read_b128 v[38:41], v191 offset:192
	ds_read_b128 v[42:45], v190 offset:224
	ds_read2st64_b32 v[32:33], v55 offset1:1
	s_waitcnt lgkmcnt(2)
	v_mfma_f32_32x32x16_bf16 v[2:17], v[34:37], v[38:41], v[2:17]
	ds_read_b128 v[34:37], v191 offset:224
	s_waitcnt lgkmcnt(1)
	v_sub_f32_e32 v38, v136, v32
	v_mul_f32_e32 v38, 0x3fb8aa3b, v38
	s_waitcnt lgkmcnt(0)
	v_mfma_f32_32x32x16_bf16 v[2:17], v[42:45], v[34:37], v[2:17]
	v_sub_f32_e32 v34, v137, v33
	v_mul_f32_e32 v34, 0x3fb8aa3b, v34
	v_exp_f32_e32 v35, v38
	v_exp_f32_e32 v34, v34
	s_cbranch_vccz .LBB0_211
	s_nop 6
	v_mul_f32_e32 v36, 0x3db504f3, v2
	v_mul_f32_e32 v37, v36, v35
	v_mul_f32_e32 v36, v36, v34
	v_readlane_b32 s46, v255, 15
	v_cvt_pk_bf16_f32 v37, v37, s0
	v_cvt_pk_bf16_f32 v36, v36, s0
	v_readlane_b32 s47, v255, 16
	v_cndmask_b32_e64 v37, v37, 0, s[6:7]
	ds_write_b16 v228, v37
	v_cndmask_b32_e64 v36, v36, 0, s[46:47]
	ds_write_b16 v229, v36
	s_mov_b64 s[46:47], 0
.LBB0_211:
	s_andn2_b64 vcc, exec, s[46:47]
	s_cbranch_vccnz .LBB0_217
	s_nop 1
	s_nop 1
	v_readlane_b32 s46, v255, 15
	v_readlane_b32 s47, v255, 16
	v_mul_f32_e32 v44, v2, v178
	v_mul_f32_e32 v45, v2, v179
	v_mul_f32_e32 v44, v35, v44
	v_mul_f32_e32 v45, v34, v45
	v_cndmask_b32_e64 v44, 0, v44, s[46:47]
	v_cndmask_b32_e64 v45, 0, v45, s[6:7]
	ds_write_b32 v192, v44
	ds_write_b32 v73, v45
.LBB0_217:
	s_andn2_b64 vcc, exec, s[4:5]
	s_mov_b64 s[46:47], -1
	s_nop 0
	v_sub_f32_e32 v2, v138, v32
	v_sub_f32_e32 v34, v139, v33
	v_mul_f32_e32 v2, 0x3fb8aa3b, v2
	v_mul_f32_e32 v35, 0x3fb8aa3b, v34
	v_exp_f32_e32 v34, v2
	v_exp_f32_e32 v2, v35
	v_cndmask_b32_e64 v35, 0, 1, s[4:5]
	v_cmp_ne_u32_e64 s[94:95], 1, v35
	s_cbranch_vccnz .LBB0_219
	v_mul_f32_e32 v35, 0x3db504f3, v3
	v_mul_f32_e32 v36, v35, v34
	v_mul_f32_e32 v35, v35, v2
	v_readlane_b32 s46, v255, 17
	v_cvt_pk_bf16_f32 v36, v36, s0
	v_readlane_b32 s47, v255, 18
	v_cvt_pk_bf16_f32 v35, v35, s0
	v_cndmask_b32_e64 v35, 0, v35, s[6:7]
	v_cndmask_b32_e64 v36, v36, 0, s[46:47]
	s_mov_b64 s[46:47], 0
	ds_write_b16 v228, v36 offset:144
	ds_write_b16 v229, v35 offset:144
.LBB0_219:
	s_andn2_b64 vcc, exec, s[46:47]
	s_cbranch_vccnz .LBB0_225
	v_readlane_b32 s46, v255, 13
	v_readlane_b32 s47, v255, 14
	v_readlane_b32 s48, v255, 17
	v_readlane_b32 s49, v255, 18
	v_mul_f32_e32 v44, v3, v180
	v_mul_f32_e32 v45, v3, v181
	v_mul_f32_e32 v44, v34, v44
	v_mul_f32_e32 v45, v2, v45
	v_cndmask_b32_e64 v44, 0, v44, s[46:47]
	v_cndmask_b32_e64 v45, 0, v45, s[48:49]
	ds_write_b32 v193, v44
	ds_write_b32 v75, v45
.LBB0_225:
	s_and_b64 vcc, exec, s[94:95]
	s_mov_b64 s[46:47], -1
	v_sub_f32_e32 v2, v140, v32
	v_sub_f32_e32 v3, v141, v33
	v_mul_f32_e32 v2, 0x3fb8aa3b, v2
	v_mul_f32_e32 v34, 0x3fb8aa3b, v3
	v_exp_f32_e32 v3, v2
	v_exp_f32_e32 v2, v34
	s_cbranch_vccnz .LBB0_227
	v_mul_f32_e32 v34, 0x3db504f3, v4
	v_mul_f32_e32 v35, v34, v3
	v_readlane_b32 s46, v255, 19
	v_cvt_pk_bf16_f32 v35, v35, s0
	v_readlane_b32 s47, v255, 20
	v_mul_f32_e32 v34, v34, v2
	v_cvt_pk_bf16_f32 v34, v34, s0
	v_cndmask_b32_e64 v35, v35, 0, s[46:47]
	v_readlane_b32 s46, v255, 21
	v_readlane_b32 s47, v255, 22
	ds_write_b16 v228, v35 offset:288
	s_nop 0
	v_cndmask_b32_e64 v34, v34, 0, s[46:47]
	s_mov_b64 s[46:47], 0
	ds_write_b16 v229, v34 offset:288
; #define LAS __attribute__((address_space(3)))
; __device__ __forceinline__ unsigned pkbf(float a, float b) { bf16x2_t v = __builtin_convertvector((f32x2_t){a, b}, bf16x2_t); return __builtin_bit_cast(unsigned, v); }
; __device__ __forceinline__ void gdn_prep_phase(LAS unsigned char* lds, const GdnPrepArgs& A, int bid, int G, const unsigned char* zero_page) {
;     ...
; #pragma unroll
;         for (int reg = 0; reg < 16; ++reg) {
;             const int i = 32 * rt + (reg & 3) + 8 * (reg >> 2) + 4 * hh; const float val = acc[reg];
;             const float ef = __expf(sc[i] - gfj), eb = __expf(sc[64 + i] - gbj);
;             if (which == 0) {
;                 const float lf = (i > j) ? sc[128 + i] * val * ef : 0.f, lb = (i < j) ? sc[192 + i] * val * eb : 0.f;
;                 ((LAS float*)(lds + L_LPF))[i * 64 + (j & 3) * 16 + (j >> 2)] = lf;
;                 const int i2 = 63 - i, j2 = 63 - j;
;                 ((LAS float*)(lds + L_LPB))[i2 * 64 + (j2 & 3) * 16 + (j2 >> 2)] = lb;
;             } else {
;                 const float af = (i >= j) ? QSCALE * val * ef : 0.f, ab = (i <= j) ? QSCALE * val * eb : 0.f;
;                 *(LAS unsigned short*)(lds + L_AF + i * AS_ + j * 2) = (unsigned short)(pkbf(af, 0.f) & 0xffffu);
;                 *(LAS unsigned short*)(lds + L_AB + i * AS_ + j * 2) = (unsigned short)(pkbf(ab, 0.f) & 0xffffu);
;             }
.LBB0_227:
	s_andn2_b64 vcc, exec, s[46:47]
	s_cbranch_vccnz .LBB0_233
	v_readlane_b32 s46, v255, 21
	v_readlane_b32 s47, v255, 22
	v_readlane_b32 s48, v255, 19
	v_readlane_b32 s49, v255, 20
	v_mul_f32_e32 v44, v4, v182
	v_mul_f32_e32 v45, v4, v183
	v_mul_f32_e32 v44, v3, v44
	v_mul_f32_e32 v45, v2, v45
	v_cndmask_b32_e64 v44, 0, v44, s[46:47]
	v_cndmask_b32_e64 v45, 0, v45, s[48:49]
	ds_write_b32 v194, v44
	ds_write_b32 v77, v45
.LBB0_233:
	s_and_b64 vcc, exec, s[94:95]
	s_mov_b64 s[46:47], -1
	v_sub_f32_e32 v2, v142, v32
	v_sub_f32_e32 v3, v143, v33
	v_mul_f32_e32 v2, 0x3fb8aa3b, v2
	v_mul_f32_e32 v4, 0x3fb8aa3b, v3
	v_exp_f32_e32 v3, v2
	v_exp_f32_e32 v2, v4
	s_cbranch_vccnz .LBB0_235
	v_mul_f32_e32 v4, 0x3db504f3, v5
	v_mul_f32_e32 v34, v4, v3
	v_readlane_b32 s46, v255, 23
	v_cvt_pk_bf16_f32 v34, v34, s0
	v_readlane_b32 s47, v255, 24
	v_mul_f32_e32 v4, v4, v2
	v_cvt_pk_bf16_f32 v4, v4, s0
	v_cndmask_b32_e64 v34, v34, 0, s[46:47]
	v_readlane_b32 s46, v255, 25
	v_readlane_b32 s47, v255, 26
	ds_write_b16 v228, v34 offset:432
	s_nop 0
	v_cndmask_b32_e64 v4, v4, 0, s[46:47]
	s_mov_b64 s[46:47], 0
	ds_write_b16 v229, v4 offset:432
.LBB0_235:
	s_andn2_b64 vcc, exec, s[46:47]
	s_cbranch_vccnz .LBB0_241
	v_readlane_b32 s46, v255, 25
	v_readlane_b32 s47, v255, 26
	v_readlane_b32 s48, v255, 23
	v_readlane_b32 s49, v255, 24
	v_mul_f32_e32 v44, v5, v230
	v_mul_f32_e32 v45, v5, v231
	v_mul_f32_e32 v44, v3, v44
	v_mul_f32_e32 v45, v2, v45
	v_cndmask_b32_e64 v44, 0, v44, s[46:47]
	v_cndmask_b32_e64 v45, 0, v45, s[48:49]
	ds_write_b32 v195, v44
	ds_write_b32 v79, v45
.LBB0_241:
	s_and_b64 vcc, exec, s[94:95]
	s_mov_b64 s[46:47], -1
	v_sub_f32_e32 v2, v144, v32
	v_sub_f32_e32 v3, v145, v33
	v_mul_f32_e32 v2, 0x3fb8aa3b, v2
	v_mul_f32_e32 v4, 0x3fb8aa3b, v3
	v_exp_f32_e32 v3, v2
	v_exp_f32_e32 v2, v4
	s_cbranch_vccnz .LBB0_243
	v_mul_f32_e32 v4, 0x3db504f3, v6
	v_mul_f32_e32 v5, v4, v3
	v_readlane_b32 s46, v255, 27
	v_cvt_pk_bf16_f32 v5, v5, s0
	v_readlane_b32 s47, v255, 28
	v_mul_f32_e32 v4, v4, v2
	v_cvt_pk_bf16_f32 v4, v4, s0
	v_cndmask_b32_e64 v5, v5, 0, s[46:47]
	v_readlane_b32 s46, v255, 29
	v_readlane_b32 s47, v255, 30
	ds_write_b16 v228, v5 offset:1152
	s_nop 0
	v_cndmask_b32_e64 v4, v4, 0, s[46:47]
	s_mov_b64 s[46:47], 0
	ds_write_b16 v229, v4 offset:1152
.LBB0_243:
	s_andn2_b64 vcc, exec, s[46:47]
	s_cbranch_vccnz .LBB0_249
	v_readlane_b32 s46, v255, 29
	v_readlane_b32 s47, v255, 30
	v_readlane_b32 s48, v255, 27
	v_readlane_b32 s49, v255, 28
	v_mul_f32_e32 v44, v6, v232
	v_mul_f32_e32 v45, v6, v233
	v_mul_f32_e32 v44, v3, v44
	v_mul_f32_e32 v45, v2, v45
	v_cndmask_b32_e64 v44, 0, v44, s[46:47]
	v_cndmask_b32_e64 v45, 0, v45, s[48:49]
	ds_write_b32 v196, v44
	ds_write_b32 v81, v45
.LBB0_249:
	s_and_b64 vcc, exec, s[94:95]
	s_mov_b64 s[46:47], -1
	v_sub_f32_e32 v2, v146, v32
	v_sub_f32_e32 v3, v147, v33
	v_mul_f32_e32 v2, 0x3fb8aa3b, v2
	v_mul_f32_e32 v4, 0x3fb8aa3b, v3
	v_exp_f32_e32 v3, v2
	v_exp_f32_e32 v2, v4
	s_cbranch_vccnz .LBB0_251
	v_mul_f32_e32 v4, 0x3db504f3, v7
	v_mul_f32_e32 v5, v4, v3
	v_readlane_b32 s46, v255, 31
	v_cvt_pk_bf16_f32 v5, v5, s0
	v_readlane_b32 s47, v255, 32
	v_mul_f32_e32 v4, v4, v2
	v_cvt_pk_bf16_f32 v4, v4, s0
	v_cndmask_b32_e64 v5, v5, 0, s[46:47]
	v_readlane_b32 s46, v255, 33
	v_readlane_b32 s47, v255, 34
	ds_write_b16 v228, v5 offset:1296
	s_nop 0
	v_cndmask_b32_e64 v4, v4, 0, s[46:47]
	s_mov_b64 s[46:47], 0
	ds_write_b16 v229, v4 offset:1296
.LBB0_251:
	s_andn2_b64 vcc, exec, s[46:47]
	s_cbranch_vccnz .LBB0_257
	v_readlane_b32 s46, v255, 33
	v_readlane_b32 s47, v255, 34
	v_readlane_b32 s48, v255, 31
	v_readlane_b32 s49, v255, 32
	v_mul_f32_e32 v44, v7, v234
	v_mul_f32_e32 v45, v7, v235
	v_mul_f32_e32 v44, v3, v44
	v_mul_f32_e32 v45, v2, v45
	v_cndmask_b32_e64 v44, 0, v44, s[46:47]
	v_cndmask_b32_e64 v45, 0, v45, s[48:49]
	ds_write_b32 v197, v44
	ds_write_b32 v83, v45
.LBB0_257:
	s_and_b64 vcc, exec, s[94:95]
	s_mov_b64 s[46:47], -1
	v_sub_f32_e32 v2, v148, v32
	v_sub_f32_e32 v3, v149, v33
	v_mul_f32_e32 v2, 0x3fb8aa3b, v2
	v_mul_f32_e32 v4, 0x3fb8aa3b, v3
	v_exp_f32_e32 v3, v2
	v_exp_f32_e32 v2, v4
	s_cbranch_vccnz .LBB0_259
	v_mul_f32_e32 v4, 0x3db504f3, v8
	v_mul_f32_e32 v5, v4, v3
	v_readlane_b32 s46, v255, 35
	v_cvt_pk_bf16_f32 v5, v5, s0
	v_readlane_b32 s47, v255, 36
	v_mul_f32_e32 v4, v4, v2
	v_cvt_pk_bf16_f32 v4, v4, s0
	v_cndmask_b32_e64 v5, v5, 0, s[46:47]
	v_readlane_b32 s46, v255, 37
	v_readlane_b32 s47, v255, 38
	ds_write_b16 v228, v5 offset:1440
	s_nop 0
	v_cndmask_b32_e64 v4, v4, 0, s[46:47]
	s_mov_b64 s[46:47], 0
	ds_write_b16 v229, v4 offset:1440
.LBB0_259:
	s_andn2_b64 vcc, exec, s[46:47]
	s_cbranch_vccnz .LBB0_265
	v_readlane_b32 s46, v255, 37
	v_readlane_b32 s47, v255, 38
	v_readlane_b32 s48, v255, 35
	v_readlane_b32 s49, v255, 36
	v_mul_f32_e32 v44, v8, v236
	v_mul_f32_e32 v45, v8, v237
	v_mul_f32_e32 v44, v3, v44
	v_mul_f32_e32 v45, v2, v45
	v_cndmask_b32_e64 v44, 0, v44, s[46:47]
	v_cndmask_b32_e64 v45, 0, v45, s[48:49]
	ds_write_b32 v198, v44
	ds_write_b32 v85, v45
; #define LAS __attribute__((address_space(3)))
; __device__ __forceinline__ unsigned pkbf(float a, float b) { bf16x2_t v = __builtin_convertvector((f32x2_t){a, b}, bf16x2_t); return __builtin_bit_cast(unsigned, v); }
; __device__ __forceinline__ void gdn_prep_phase(LAS unsigned char* lds, const GdnPrepArgs& A, int bid, int G, const unsigned char* zero_page) {
;     ...
; #pragma unroll
;         for (int reg = 0; reg < 16; ++reg) {
;             const int i = 32 * rt + (reg & 3) + 8 * (reg >> 2) + 4 * hh; const float val = acc[reg];
;             const float ef = __expf(sc[i] - gfj), eb = __expf(sc[64 + i] - gbj);
;             if (which == 0) {
;                 const float lf = (i > j) ? sc[128 + i] * val * ef : 0.f, lb = (i < j) ? sc[192 + i] * val * eb : 0.f;
;                 ((LAS float*)(lds + L_LPF))[i * 64 + (j & 3) * 16 + (j >> 2)] = lf;
;                 const int i2 = 63 - i, j2 = 63 - j;
;                 ((LAS float*)(lds + L_LPB))[i2 * 64 + (j2 & 3) * 16 + (j2 >> 2)] = lb;
;             } else {
;                 const float af = (i >= j) ? QSCALE * val * ef : 0.f, ab = (i <= j) ? QSCALE * val * eb : 0.f;
;                 *(LAS unsigned short*)(lds + L_AF + i * AS_ + j * 2) = (unsigned short)(pkbf(af, 0.f) & 0xffffu);
;                 *(LAS unsigned short*)(lds + L_AB + i * AS_ + j * 2) = (unsigned short)(pkbf(ab, 0.f) & 0xffffu);
;             }
.LBB0_265:
	s_and_b64 vcc, exec, s[94:95]
	s_mov_b64 s[46:47], -1
	v_sub_f32_e32 v2, v150, v32
	v_sub_f32_e32 v3, v151, v33
	v_mul_f32_e32 v2, 0x3fb8aa3b, v2
	v_mul_f32_e32 v4, 0x3fb8aa3b, v3
	v_exp_f32_e32 v3, v2
	v_exp_f32_e32 v2, v4
	s_cbranch_vccnz .LBB0_267
	v_mul_f32_e32 v4, 0x3db504f3, v9
	v_mul_f32_e32 v5, v4, v3
	v_readlane_b32 s46, v255, 39
	v_cvt_pk_bf16_f32 v5, v5, s0
	v_readlane_b32 s47, v255, 40
	v_mul_f32_e32 v4, v4, v2
	v_cvt_pk_bf16_f32 v4, v4, s0
	v_cndmask_b32_e64 v5, v5, 0, s[46:47]
	v_readlane_b32 s46, v255, 41
	v_readlane_b32 s47, v255, 42
	ds_write_b16 v228, v5 offset:1584
	s_nop 0
	v_cndmask_b32_e64 v4, v4, 0, s[46:47]
	s_mov_b64 s[46:47], 0
	ds_write_b16 v229, v4 offset:1584
.LBB0_267:
	s_andn2_b64 vcc, exec, s[46:47]
	s_cbranch_vccnz .LBB0_273
	v_readlane_b32 s46, v255, 41
	v_readlane_b32 s47, v255, 42
	v_readlane_b32 s48, v255, 39
	v_readlane_b32 s49, v255, 40
	v_mul_f32_e32 v44, v9, v238
	v_mul_f32_e32 v45, v9, v239
	v_mul_f32_e32 v44, v3, v44
	v_mul_f32_e32 v45, v2, v45
	v_cndmask_b32_e64 v44, 0, v44, s[46:47]
	v_cndmask_b32_e64 v45, 0, v45, s[48:49]
	ds_write_b32 v199, v44
	ds_write_b32 v87, v45
.LBB0_273:
	s_and_b64 vcc, exec, s[94:95]
	s_mov_b64 s[46:47], -1
	v_sub_f32_e32 v2, v152, v32
	v_sub_f32_e32 v3, v153, v33
	v_mul_f32_e32 v2, 0x3fb8aa3b, v2
	v_mul_f32_e32 v4, 0x3fb8aa3b, v3
	v_exp_f32_e32 v3, v2
	v_exp_f32_e32 v2, v4
	s_cbranch_vccnz .LBB0_275
	v_mul_f32_e32 v4, 0x3db504f3, v10
	v_mul_f32_e32 v5, v4, v3
	v_readlane_b32 s46, v255, 43
	v_cvt_pk_bf16_f32 v5, v5, s0
	v_readlane_b32 s47, v255, 44
	v_mul_f32_e32 v4, v4, v2
	v_cvt_pk_bf16_f32 v4, v4, s0
	v_cndmask_b32_e64 v5, v5, 0, s[46:47]
	v_readlane_b32 s46, v255, 45
	v_readlane_b32 s47, v255, 46
	ds_write_b16 v228, v5 offset:2304
	s_nop 0
	v_cndmask_b32_e64 v4, v4, 0, s[46:47]
	s_mov_b64 s[46:47], 0
	ds_write_b16 v229, v4 offset:2304
.LBB0_275:
	s_andn2_b64 vcc, exec, s[46:47]
	s_cbranch_vccnz .LBB0_281
	v_readlane_b32 s46, v255, 45
	v_readlane_b32 s47, v255, 46
	v_readlane_b32 s48, v255, 43
	v_readlane_b32 s49, v255, 44
	v_mul_f32_e32 v44, v10, v240
	v_mul_f32_e32 v45, v10, v241
	v_mul_f32_e32 v44, v3, v44
	v_mul_f32_e32 v45, v2, v45
	v_cndmask_b32_e64 v44, 0, v44, s[46:47]
	v_cndmask_b32_e64 v45, 0, v45, s[48:49]
	ds_write_b32 v200, v44
	ds_write_b32 v89, v45
.LBB0_281:
	s_and_b64 vcc, exec, s[94:95]
	s_mov_b64 s[46:47], -1
	v_sub_f32_e32 v2, v154, v32
	v_sub_f32_e32 v3, v155, v33
	v_mul_f32_e32 v2, 0x3fb8aa3b, v2
	v_mul_f32_e32 v4, 0x3fb8aa3b, v3
	v_exp_f32_e32 v3, v2
	v_exp_f32_e32 v2, v4
	s_cbranch_vccnz .LBB0_283
	v_mul_f32_e32 v4, 0x3db504f3, v11
	v_mul_f32_e32 v5, v4, v3
	v_mul_f32_e32 v4, v4, v2
	v_cvt_pk_bf16_f32 v5, v5, s0
	v_cvt_pk_bf16_f32 v4, v4, s0
	v_cndmask_b32_e64 v5, v5, 0, s[74:75]
	v_cndmask_b32_e64 v4, v4, 0, s[76:77]
	s_mov_b64 s[46:47], 0
	ds_write_b16 v228, v5 offset:2448
	ds_write_b16 v229, v4 offset:2448
.LBB0_283:
	s_andn2_b64 vcc, exec, s[46:47]
	s_cbranch_vccnz .LBB0_289
	v_mul_f32_e32 v44, v11, v242
	v_mul_f32_e32 v45, v11, v243
	v_mul_f32_e32 v44, v3, v44
	v_mul_f32_e32 v45, v2, v45
	v_cndmask_b32_e64 v44, 0, v44, s[76:77]
	v_cndmask_b32_e64 v45, 0, v45, s[74:75]
	ds_write_b32 v201, v44
	ds_write_b32 v91, v45
.LBB0_289:
	s_and_b64 vcc, exec, s[94:95]
	s_mov_b64 s[46:47], -1
	v_sub_f32_e32 v2, v156, v32
	v_sub_f32_e32 v3, v157, v33
	v_mul_f32_e32 v2, 0x3fb8aa3b, v2
	v_mul_f32_e32 v4, 0x3fb8aa3b, v3
	v_exp_f32_e32 v3, v2
	v_exp_f32_e32 v2, v4
	s_cbranch_vccnz .LBB0_291
	v_mul_f32_e32 v4, 0x3db504f3, v12
	v_mul_f32_e32 v5, v4, v3
	v_mul_f32_e32 v4, v4, v2
	v_cvt_pk_bf16_f32 v5, v5, s0
	v_cvt_pk_bf16_f32 v4, v4, s0
	v_cndmask_b32_e64 v5, v5, 0, s[58:59]
	v_cndmask_b32_e64 v4, v4, 0, s[60:61]
	s_mov_b64 s[46:47], 0
	ds_write_b16 v228, v5 offset:2592
	ds_write_b16 v229, v4 offset:2592
.LBB0_291:
	s_andn2_b64 vcc, exec, s[46:47]
	s_cbranch_vccnz .LBB0_297
	v_mul_f32_e32 v44, v12, v244
	v_mul_f32_e32 v45, v12, v245
	v_mul_f32_e32 v44, v3, v44
	v_mul_f32_e32 v45, v2, v45
	v_cndmask_b32_e64 v44, 0, v44, s[60:61]
	v_cndmask_b32_e64 v45, 0, v45, s[58:59]
	ds_write_b32 v202, v44
	ds_write_b32 v93, v45
.LBB0_297:
	s_and_b64 vcc, exec, s[94:95]
	s_mov_b64 s[46:47], -1
	v_sub_f32_e32 v2, v158, v32
	v_sub_f32_e32 v3, v159, v33
	v_mul_f32_e32 v2, 0x3fb8aa3b, v2
	v_mul_f32_e32 v4, 0x3fb8aa3b, v3
	v_exp_f32_e32 v3, v2
	v_exp_f32_e32 v2, v4
	s_cbranch_vccnz .LBB0_299
	v_mul_f32_e32 v4, 0x3db504f3, v13
	v_mul_f32_e32 v5, v4, v3
	v_mul_f32_e32 v4, v4, v2
	v_cvt_pk_bf16_f32 v5, v5, s0
	v_cvt_pk_bf16_f32 v4, v4, s0
	v_cndmask_b32_e64 v5, v5, 0, s[62:63]
	v_cndmask_b32_e64 v4, v4, 0, s[64:65]
	s_mov_b64 s[46:47], 0
	ds_write_b16 v228, v5 offset:2736
	ds_write_b16 v229, v4 offset:2736
.LBB0_299:
	s_andn2_b64 vcc, exec, s[46:47]
	s_cbranch_vccnz .LBB0_305
	v_mul_f32_e32 v44, v13, v248
	v_mul_f32_e32 v45, v13, v249
	v_mul_f32_e32 v44, v3, v44
	v_mul_f32_e32 v45, v2, v45
	v_cndmask_b32_e64 v44, 0, v44, s[64:65]
	v_cndmask_b32_e64 v45, 0, v45, s[62:63]
	ds_write_b32 v203, v44
	ds_write_b32 v95, v45
.LBB0_305:
	s_and_b64 vcc, exec, s[94:95]
	s_mov_b64 s[46:47], -1
	v_sub_f32_e32 v2, v160, v32
	v_sub_f32_e32 v3, v161, v33
	v_mul_f32_e32 v2, 0x3fb8aa3b, v2
	v_mul_f32_e32 v4, 0x3fb8aa3b, v3
	v_exp_f32_e32 v3, v2
	v_exp_f32_e32 v2, v4
	s_cbranch_vccnz .LBB0_307
	v_mul_f32_e32 v4, 0x3db504f3, v14
	v_mul_f32_e32 v5, v4, v3
	v_mul_f32_e32 v4, v4, v2
	v_cvt_pk_bf16_f32 v5, v5, s0
	v_cvt_pk_bf16_f32 v4, v4, s0
	v_cndmask_b32_e64 v5, v5, 0, s[84:85]
	v_cndmask_b32_e64 v4, v4, 0, s[78:79]
	s_mov_b64 s[46:47], 0
	ds_write_b16 v228, v5 offset:3456
	ds_write_b16 v229, v4 offset:3456

; #define LAS __attribute__((address_space(3)))
; __device__ __forceinline__ unsigned pkbf(float a, float b) { bf16x2_t v = __builtin_convertvector((f32x2_t){a, b}, bf16x2_t); return __builtin_bit_cast(unsigned, v); }
; __device__ __forceinline__ void gdn_prep_phase(LAS unsigned char* lds, const GdnPrepArgs& A, int bid, int G, const unsigned char* zero_page) {
;     ...
;             const float ef = __expf(sc[i] - gfj), eb = __expf(sc[64 + i] - gbj);
;             if (which == 0) {
;                 const float lf = (i > j) ? sc[128 + i] * val * ef : 0.f, lb = (i < j) ? sc[192 + i] * val * eb : 0.f;
;                 ((LAS float*)(lds + L_LPF))[i * 64 + (j & 3) * 16 + (j >> 2)] = lf;
;                 const int i2 = 63 - i, j2 = 63 - j;
;                 ((LAS float*)(lds + L_LPB))[i2 * 64 + (j2 & 3) * 16 + (j2 >> 2)] = lb;
;             } else {
;                 const float af = (i >= j) ? QSCALE * val * ef : 0.f, ab = (i <= j) ? QSCALE * val * eb : 0.f;
;                 *(LAS unsigned short*)(lds + L_AF + i * AS_ + j * 2) = (unsigned short)(pkbf(af, 0.f) & 0xffffu);
;                 *(LAS unsigned short*)(lds + L_AB + i * AS_ + j * 2) = (unsigned short)(pkbf(ab, 0.f) & 0xffffu);
.LBB0_313:
	s_and_b64 vcc, exec, s[94:95]
	s_mov_b64 s[46:47], -1
	v_sub_f32_e32 v2, v162, v32
	v_sub_f32_e32 v3, v163, v33
	v_mul_f32_e32 v2, 0x3fb8aa3b, v2
	v_mul_f32_e32 v4, 0x3fb8aa3b, v3
	v_exp_f32_e32 v3, v2
	v_exp_f32_e32 v2, v4
	s_cbranch_vccnz .LBB0_315
	v_mul_f32_e32 v4, 0x3db504f3, v15
	v_mul_f32_e32 v5, v4, v3
	v_mul_f32_e32 v4, v4, v2
	v_cvt_pk_bf16_f32 v5, v5, s0
	v_cvt_pk_bf16_f32 v4, v4, s0
	v_cndmask_b32_e64 v5, v5, 0, s[80:81]
	v_cndmask_b32_e64 v4, v4, 0, s[26:27]
	s_mov_b64 s[46:47], 0
	ds_write_b16 v228, v5 offset:3600
	ds_write_b16 v229, v4 offset:3600

; #define LAS __attribute__((address_space(3)))
; __device__ __forceinline__ unsigned pkbf(float a, float b) { bf16x2_t v = __builtin_convertvector((f32x2_t){a, b}, bf16x2_t); return __builtin_bit_cast(unsigned, v); }
; __device__ __forceinline__ void gdn_prep_phase(LAS unsigned char* lds, const GdnPrepArgs& A, int bid, int G, const unsigned char* zero_page) {
;     ...
;             const float ef = __expf(sc[i] - gfj), eb = __expf(sc[64 + i] - gbj);
;             if (which == 0) {
;                 const float lf = (i > j) ? sc[128 + i] * val * ef : 0.f, lb = (i < j) ? sc[192 + i] * val * eb : 0.f;
;                 ((LAS float*)(lds + L_LPF))[i * 64 + (j & 3) * 16 + (j >> 2)] = lf;
;                 const int i2 = 63 - i, j2 = 63 - j;
;                 ((LAS float*)(lds + L_LPB))[i2 * 64 + (j2 & 3) * 16 + (j2 >> 2)] = lb;
;             } else {
;                 const float af = (i >= j) ? QSCALE * val * ef : 0.f, ab = (i <= j) ? QSCALE * val * eb : 0.f;
;                 *(LAS unsigned short*)(lds + L_AF + i * AS_ + j * 2) = (unsigned short)(pkbf(af, 0.f) & 0xffffu);
;                 *(LAS unsigned short*)(lds + L_AB + i * AS_ + j * 2) = (unsigned short)(pkbf(ab, 0.f) & 0xffffu);
.LBB0_321:
	s_and_b64 vcc, exec, s[94:95]
	s_mov_b64 s[46:47], -1
	v_sub_f32_e32 v2, v174, v32
	v_sub_f32_e32 v3, v175, v33
	v_mul_f32_e32 v2, 0x3fb8aa3b, v2
	v_mul_f32_e32 v4, 0x3fb8aa3b, v3
	v_exp_f32_e32 v3, v2
	v_exp_f32_e32 v2, v4
	s_cbranch_vccnz .LBB0_323
	v_mul_f32_e32 v4, 0x3db504f3, v16
	v_mul_f32_e32 v5, v4, v3
	v_mul_f32_e32 v4, v4, v2
	v_cvt_pk_bf16_f32 v5, v5, s0
	v_cvt_pk_bf16_f32 v4, v4, s0
	v_cndmask_b32_e64 v5, v5, 0, s[28:29]
	v_cndmask_b32_e64 v4, v4, 0, s[30:31]
	s_mov_b64 s[46:47], 0
	ds_write_b16 v228, v5 offset:3744
	ds_write_b16 v229, v4 offset:3744

; #define LAS __attribute__((address_space(3)))
; __device__ __forceinline__ unsigned pkbf(float a, float b) { bf16x2_t v = __builtin_convertvector((f32x2_t){a, b}, bf16x2_t); return __builtin_bit_cast(unsigned, v); }
; __device__ __forceinline__ void gdn_prep_phase(LAS unsigned char* lds, const GdnPrepArgs& A, int bid, int G, const unsigned char* zero_page) {
;     ...
;             const float ef = __expf(sc[i] - gfj), eb = __expf(sc[64 + i] - gbj);
;             if (which == 0) {
;                 const float lf = (i > j) ? sc[128 + i] * val * ef : 0.f, lb = (i < j) ? sc[192 + i] * val * eb : 0.f;
;                 ((LAS float*)(lds + L_LPF))[i * 64 + (j & 3) * 16 + (j >> 2)] = lf;
;                 const int i2 = 63 - i, j2 = 63 - j;
;                 ((LAS float*)(lds + L_LPB))[i2 * 64 + (j2 & 3) * 16 + (j2 >> 2)] = lb;
;             } else {
;                 const float af = (i >= j) ? QSCALE * val * ef : 0.f, ab = (i <= j) ? QSCALE * val * eb : 0.f;
;                 *(LAS unsigned short*)(lds + L_AF + i * AS_ + j * 2) = (unsigned short)(pkbf(af, 0.f) & 0xffffu);
;                 *(LAS unsigned short*)(lds + L_AB + i * AS_ + j * 2) = (unsigned short)(pkbf(ab, 0.f) & 0xffffu);
.LBB0_329:
	s_and_b64 vcc, exec, s[94:95]
	s_mov_b64 s[46:47], -1
	v_sub_f32_e32 v2, v176, v32
	v_sub_f32_e32 v3, v177, v33
	v_mul_f32_e32 v2, 0x3fb8aa3b, v2
	v_mul_f32_e32 v4, 0x3fb8aa3b, v3
	v_exp_f32_e32 v3, v2
	v_exp_f32_e32 v2, v4
	s_cbranch_vccnz .LBB0_331
	v_mul_f32_e32 v4, 0x3db504f3, v17
	v_mul_f32_e32 v5, v4, v3
	v_mul_f32_e32 v4, v4, v2
	v_cvt_pk_bf16_f32 v5, v5, s0
	v_cvt_pk_bf16_f32 v4, v4, s0
	v_cndmask_b32_e64 v5, v5, 0, s[24:25]
	v_cndmask_b32_e64 v4, v4, 0, s[36:37]
	s_mov_b64 s[46:47], 0
	ds_write_b16 v228, v5 offset:3888
	ds_write_b16 v229, v4 offset:3888
